# mLSTM chunk-state phase: each wave's 32x128 bf16 state block staged through a private LDS tile and stored as 8 x 16-byte rows instead of 64 scattered 2-byte stores per lane
# speedup vs baseline: 1.0002x; 1.0002x over previous
.LBB0_1072:
	v_lshl_add_u64 v[82:83], s[62:63], 0, v[78:79]
	v_add_co_u32_e64 v102, s[2:3], s51, v82
	v_lshl_add_u64 v[104:105], s[62:63], 0, v[76:77]
	s_nop 0
	v_addc_co_u32_e64 v103, s[2:3], 0, v83, s[2:3]
	v_add_co_u32_e64 v106, s[2:3], 1.0, v104
	v_lshl_add_u64 v[108:109], s[62:63], 0, v[72:73]
	s_nop 0
	v_addc_co_u32_e64 v107, s[2:3], 0, v105, s[2:3]
	s_mov_b32 s2, 0x25000000
	s_nop 0
	v_add_co_u32_e64 v110, s[2:3], s2, v108
	v_lshl_add_u64 v[90:91], v[104:105], 0, s[0:1]
	s_nop 0
	v_addc_co_u32_e64 v111, s[2:3], 0, v109, s[2:3]
	s_mov_b32 s2, 0x25080000
	s_nop 0
	v_add_co_u32_e64 v112, s[2:3], s2, v108
	global_load_dwordx4 v[82:85], v[102:103], off
	s_nop 0
	v_addc_co_u32_e64 v113, s[2:3], 0, v109, s[2:3]
	global_load_dwordx4 v[86:89], v[106:107], off
	s_nop 0
	global_load_dwordx4 v[90:93], v[90:91], off offset:16
	s_mov_b32 s2, 0x25100000
	global_load_dwordx4 v[94:97], v[110:111], off
	global_load_dwordx4 v[98:101], v[112:113], off
	s_add_i32 s13, s13, -2
	v_lshl_add_u64 v[72:73], v[72:73], 0, 64
	v_lshl_add_u64 v[76:77], v[76:77], 0, s[72:73]
	v_lshl_add_u64 v[78:79], v[78:79], 0, 64
	s_cmp_eq_u32 s13, 0
	s_waitcnt vmcnt(0)
	v_and_b32_e32 v115, 0xffff0000, v94
	v_lshlrev_b32_e32 v114, 16, v98
	v_lshlrev_b32_e32 v120, 16, v99
	v_and_b32_e32 v121, 0xffff0000, v95
	v_pk_mul_f32 v[114:115], v[86:87], v[114:115]
	v_and_b32_e32 v116, 0xffff0000, v98
	v_lshlrev_b32_e32 v117, 16, v94
	v_pk_mul_f32 v[120:121], v[88:89], v[120:121]
	v_and_b32_e32 v94, 0xffff0000, v99
	v_lshlrev_b32_e32 v95, 16, v95
	v_lshlrev_b32_e32 v122, 16, v100
	v_and_b32_e32 v123, 0xffff0000, v96
	v_lshlrev_b32_e32 v128, 16, v101
	v_and_b32_e32 v129, 0xffff0000, v97
	v_pk_mul_f32 v[118:119], v[86:87], v[116:117] op_sel:[1,0] op_sel_hi:[0,1]
	v_pk_mul_f32 v[98:99], v[88:89], v[94:95] op_sel:[1,0] op_sel_hi:[0,1]
	v_pk_mul_f32 v[122:123], v[90:91], v[122:123]
	v_and_b32_e32 v124, 0xffff0000, v100
	v_lshlrev_b32_e32 v125, 16, v96
	v_pk_mul_f32 v[128:129], v[92:93], v[128:129]
	v_and_b32_e32 v96, 0xffff0000, v101
	v_lshlrev_b32_e32 v97, 16, v97
	v_pk_fma_f32 v[116:117], v[86:87], v[116:117], v[114:115] op_sel:[1,0,0] op_sel_hi:[0,1,1]
	v_pk_fma_f32 v[94:95], v[88:89], v[94:95], v[120:121] op_sel:[1,0,0] op_sel_hi:[0,1,1]
	v_pk_mul_f32 v[100:101], v[92:93], v[96:97] op_sel:[1,0] op_sel_hi:[0,1]
	v_pk_add_f32 v[94:95], v[116:117], v[94:95]
	v_pk_fma_f32 v[116:117], v[90:91], v[124:125], v[122:123] op_sel:[1,0,0] op_sel_hi:[0,1,1]
	v_pk_fma_f32 v[96:97], v[92:93], v[96:97], v[128:129] op_sel:[1,0,0] op_sel_hi:[0,1,1]
	v_pk_mul_f32 v[126:127], v[90:91], v[124:125] op_sel:[1,0] op_sel_hi:[0,1]
	v_pk_add_f32 v[96:97], v[116:117], v[96:97]
	s_nop 0
	v_pk_add_f32 v[116:117], v[94:95], v[96:97]
	v_cvt_pk_bf16_f32 v94, v119, v115
	v_cvt_pk_bf16_f32 v95, v99, v121
	v_cvt_pk_bf16_f32 v96, v127, v123
	v_cvt_pk_bf16_f32 v97, v101, v129
	v_pk_add_f32 v[80:81], v[80:81], v[116:117]
	s_nop 0
	v_mfma_f32_32x32x16_bf16 v[48:63], v[82:85], v[94:97], v[48:63]
	v_cvt_pk_bf16_f32 v94, v114, v118
	v_add_co_u32_e64 v114, s[2:3], s2, v108
	v_cvt_pk_bf16_f32 v95, v120, v98
	s_nop 0
	v_addc_co_u32_e64 v115, s[2:3], 0, v109, s[2:3]
	s_mov_b32 s2, 0x25180000
	s_nop 0
	v_add_co_u32_e64 v108, s[2:3], s2, v108
	v_cvt_pk_bf16_f32 v96, v122, v126
	v_cvt_pk_bf16_f32 v97, v128, v100
	v_addc_co_u32_e64 v109, s[2:3], 0, v109, s[2:3]
	s_nop 0
	v_mfma_f32_32x32x16_bf16 v[32:47], v[82:85], v[94:97], v[32:47]
	global_load_dwordx4 v[94:97], v[114:115], off
	global_load_dwordx4 v[98:101], v[108:109], off
	s_mov_b64 s[2:3], 0x3f800040
	s_waitcnt vmcnt(1)
	v_and_b32_e32 v117, 0xffff0000, v94
	s_waitcnt vmcnt(0)
	v_lshlrev_b32_e32 v116, 16, v98
	v_lshlrev_b32_e32 v122, 16, v99
	v_and_b32_e32 v123, 0xffff0000, v95
	v_pk_mul_f32 v[116:117], v[86:87], v[116:117]
	v_and_b32_e32 v118, 0xffff0000, v98
	v_lshlrev_b32_e32 v119, 16, v94
	v_pk_mul_f32 v[122:123], v[88:89], v[122:123]
	v_and_b32_e32 v94, 0xffff0000, v99
	v_lshlrev_b32_e32 v95, 16, v95
	v_lshlrev_b32_e32 v124, 16, v100
	v_and_b32_e32 v125, 0xffff0000, v96
	v_lshlrev_b32_e32 v130, 16, v101
	v_and_b32_e32 v131, 0xffff0000, v97
	v_pk_mul_f32 v[120:121], v[86:87], v[118:119] op_sel:[1,0] op_sel_hi:[0,1]
	v_pk_mul_f32 v[98:99], v[88:89], v[94:95] op_sel:[1,0] op_sel_hi:[0,1]
	v_pk_mul_f32 v[124:125], v[90:91], v[124:125]
	v_and_b32_e32 v126, 0xffff0000, v100
	v_lshlrev_b32_e32 v127, 16, v96
	v_pk_mul_f32 v[130:131], v[92:93], v[130:131]
	v_and_b32_e32 v96, 0xffff0000, v101
	v_lshlrev_b32_e32 v97, 16, v97
	v_pk_fma_f32 v[86:87], v[86:87], v[118:119], v[116:117] op_sel:[1,0,0] op_sel_hi:[0,1,1]
	v_pk_fma_f32 v[88:89], v[88:89], v[94:95], v[122:123] op_sel:[1,0,0] op_sel_hi:[0,1,1]
	v_pk_mul_f32 v[128:129], v[90:91], v[126:127] op_sel:[1,0] op_sel_hi:[0,1]
	v_pk_add_f32 v[86:87], v[86:87], v[88:89]
	v_pk_fma_f32 v[88:89], v[90:91], v[126:127], v[124:125] op_sel:[1,0,0] op_sel_hi:[0,1,1]
	v_pk_fma_f32 v[90:91], v[92:93], v[96:97], v[130:131] op_sel:[1,0,0] op_sel_hi:[0,1,1]
	v_pk_mul_f32 v[100:101], v[92:93], v[96:97] op_sel:[1,0] op_sel_hi:[0,1]
	v_pk_add_f32 v[88:89], v[88:89], v[90:91]
	s_nop 0
	v_pk_add_f32 v[90:91], v[86:87], v[88:89]
	v_cvt_pk_bf16_f32 v86, v121, v117
	v_cvt_pk_bf16_f32 v87, v99, v123
	v_cvt_pk_bf16_f32 v88, v129, v125
	v_cvt_pk_bf16_f32 v89, v101, v131
	v_pk_add_f32 v[74:75], v[74:75], v[90:91]
	v_lshl_add_u64 v[90:91], v[104:105], 0, s[2:3]
	v_mfma_f32_32x32x16_bf16 v[16:31], v[82:85], v[86:89], v[16:31]
	v_cvt_pk_bf16_f32 v86, v116, v120
	v_cvt_pk_bf16_f32 v87, v122, v98
	v_cvt_pk_bf16_f32 v88, v124, v128
	v_cvt_pk_bf16_f32 v89, v130, v100
	s_nop 1
	v_mfma_f32_32x32x16_bf16 v[0:15], v[82:85], v[86:89], v[0:15]
	global_load_dwordx4 v[82:85], v[102:103], off offset:32
	global_load_dwordx4 v[86:89], v[106:107], off offset:64
	s_nop 0
	global_load_dwordx4 v[90:93], v[90:91], off offset:16
	s_nop 0
	global_load_dwordx4 v[94:97], v[110:111], off offset:32
	global_load_dwordx4 v[98:101], v[112:113], off offset:32
	s_waitcnt vmcnt(1)
	v_and_b32_e32 v103, 0xffff0000, v94
	s_waitcnt vmcnt(0)
	v_lshlrev_b32_e32 v102, 16, v98
	v_lshlrev_b32_e32 v110, 16, v99
	v_and_b32_e32 v111, 0xffff0000, v95
	v_pk_mul_f32 v[102:103], v[86:87], v[102:103]
	v_and_b32_e32 v104, 0xffff0000, v98
	v_lshlrev_b32_e32 v105, 16, v94
	v_pk_mul_f32 v[110:111], v[88:89], v[110:111]
	v_and_b32_e32 v94, 0xffff0000, v99
	v_lshlrev_b32_e32 v95, 16, v95
	v_lshlrev_b32_e32 v112, 16, v100
	v_and_b32_e32 v113, 0xffff0000, v96
	v_lshlrev_b32_e32 v120, 16, v101
	v_and_b32_e32 v121, 0xffff0000, v97
	v_pk_mul_f32 v[106:107], v[86:87], v[104:105] op_sel:[1,0] op_sel_hi:[0,1]
	v_pk_mul_f32 v[98:99], v[88:89], v[94:95] op_sel:[1,0] op_sel_hi:[0,1]
	v_pk_mul_f32 v[112:113], v[90:91], v[112:113]
	v_and_b32_e32 v116, 0xffff0000, v100
	v_lshlrev_b32_e32 v117, 16, v96
	v_pk_mul_f32 v[120:121], v[92:93], v[120:121]
	v_and_b32_e32 v96, 0xffff0000, v101
	v_lshlrev_b32_e32 v97, 16, v97
	v_pk_fma_f32 v[104:105], v[86:87], v[104:105], v[102:103] op_sel:[1,0,0] op_sel_hi:[0,1,1]
	v_pk_fma_f32 v[94:95], v[88:89], v[94:95], v[110:111] op_sel:[1,0,0] op_sel_hi:[0,1,1]
	v_pk_mul_f32 v[100:101], v[92:93], v[96:97] op_sel:[1,0] op_sel_hi:[0,1]
	v_pk_add_f32 v[94:95], v[104:105], v[94:95]
	v_pk_fma_f32 v[104:105], v[90:91], v[116:117], v[112:113] op_sel:[1,0,0] op_sel_hi:[0,1,1]
	v_pk_fma_f32 v[96:97], v[92:93], v[96:97], v[120:121] op_sel:[1,0,0] op_sel_hi:[0,1,1]
	v_pk_mul_f32 v[118:119], v[90:91], v[116:117] op_sel:[1,0] op_sel_hi:[0,1]
	v_pk_add_f32 v[96:97], v[104:105], v[96:97]
	s_nop 0
	v_pk_add_f32 v[104:105], v[94:95], v[96:97]
	v_cvt_pk_bf16_f32 v94, v107, v103
	v_cvt_pk_bf16_f32 v95, v99, v111
	v_cvt_pk_bf16_f32 v96, v119, v113
	v_cvt_pk_bf16_f32 v97, v101, v121
	v_pk_add_f32 v[80:81], v[80:81], v[104:105]
	s_nop 0
	v_mfma_f32_32x32x16_bf16 v[48:63], v[82:85], v[94:97], v[48:63]
	v_cvt_pk_bf16_f32 v94, v102, v106
	v_cvt_pk_bf16_f32 v95, v110, v98
	v_cvt_pk_bf16_f32 v96, v112, v118
	v_cvt_pk_bf16_f32 v97, v120, v100
	s_nop 1
	v_mfma_f32_32x32x16_bf16 v[32:47], v[82:85], v[94:97], v[32:47]
	global_load_dwordx4 v[94:97], v[114:115], off offset:32
	global_load_dwordx4 v[98:101], v[108:109], off offset:32
	s_waitcnt vmcnt(1)
	v_and_b32_e32 v103, 0xffff0000, v94
	s_waitcnt vmcnt(0)
	v_lshlrev_b32_e32 v102, 16, v98
	v_lshlrev_b32_e32 v108, 16, v99
	v_and_b32_e32 v109, 0xffff0000, v95
	v_pk_mul_f32 v[102:103], v[86:87], v[102:103]
	v_and_b32_e32 v104, 0xffff0000, v98
	v_lshlrev_b32_e32 v105, 16, v94
	v_pk_mul_f32 v[108:109], v[88:89], v[108:109]
	v_and_b32_e32 v94, 0xffff0000, v99
	v_lshlrev_b32_e32 v95, 16, v95
	v_lshlrev_b32_e32 v110, 16, v100
	v_and_b32_e32 v111, 0xffff0000, v96
	v_lshlrev_b32_e32 v116, 16, v101
	v_and_b32_e32 v117, 0xffff0000, v97
	v_pk_mul_f32 v[106:107], v[86:87], v[104:105] op_sel:[1,0] op_sel_hi:[0,1]
	v_pk_mul_f32 v[98:99], v[88:89], v[94:95] op_sel:[1,0] op_sel_hi:[0,1]
	v_pk_mul_f32 v[110:111], v[90:91], v[110:111]
	v_and_b32_e32 v112, 0xffff0000, v100
	v_lshlrev_b32_e32 v113, 16, v96
	v_pk_mul_f32 v[116:117], v[92:93], v[116:117]
	v_and_b32_e32 v96, 0xffff0000, v101
	v_lshlrev_b32_e32 v97, 16, v97
	v_pk_fma_f32 v[86:87], v[86:87], v[104:105], v[102:103] op_sel:[1,0,0] op_sel_hi:[0,1,1]
	v_pk_fma_f32 v[88:89], v[88:89], v[94:95], v[108:109] op_sel:[1,0,0] op_sel_hi:[0,1,1]
	v_pk_mul_f32 v[114:115], v[90:91], v[112:113] op_sel:[1,0] op_sel_hi:[0,1]
	v_pk_add_f32 v[86:87], v[86:87], v[88:89]
	v_pk_fma_f32 v[88:89], v[90:91], v[112:113], v[110:111] op_sel:[1,0,0] op_sel_hi:[0,1,1]
	v_pk_fma_f32 v[90:91], v[92:93], v[96:97], v[116:117] op_sel:[1,0,0] op_sel_hi:[0,1,1]
	v_pk_mul_f32 v[100:101], v[92:93], v[96:97] op_sel:[1,0] op_sel_hi:[0,1]
	v_pk_add_f32 v[88:89], v[88:89], v[90:91]
	s_nop 0
	v_pk_add_f32 v[90:91], v[86:87], v[88:89]
	v_cvt_pk_bf16_f32 v86, v107, v103
	v_cvt_pk_bf16_f32 v87, v99, v109
	v_cvt_pk_bf16_f32 v88, v115, v111
	v_cvt_pk_bf16_f32 v89, v101, v117
	v_pk_add_f32 v[74:75], v[74:75], v[90:91]
	s_nop 0
	v_mfma_f32_32x32x16_bf16 v[16:31], v[82:85], v[86:89], v[16:31]
	v_cvt_pk_bf16_f32 v86, v102, v106
	v_cvt_pk_bf16_f32 v87, v108, v98
	v_cvt_pk_bf16_f32 v88, v110, v114
	v_cvt_pk_bf16_f32 v89, v116, v100
	s_nop 1
	v_mfma_f32_32x32x16_bf16 v[0:15], v[82:85], v[86:89], v[0:15]
	s_cbranch_scc0 .LBB0_1072
	s_and_b32 s3, s4, 3
	s_and_b32 s4, s12, 0x1fffffc
	s_or_b32 s3, s4, s3
	s_lshl_b32 s4, s6, 4
	s_and_b32 s2, s5, 63
	s_and_b32 s4, s4, 64
	s_lshl_b32 s3, s3, 7
	s_or_b32 s2, s2, s4
	s_or_b32 s2, s2, s3
	s_ashr_i32 s3, s2, 31
	s_lshl_b64 s[4:5], s[2:3], 15
	v_lshl_add_u64 v[72:73], v[66:67], 0, s[4:5]
	v_mov_b64_e32 v[76:77], v[72:73]
	v_mbcnt_lo_u32_b32 v166, -1, 0
	v_mbcnt_hi_u32_b32 v166, -1, v166
	v_and_b32_e32 v167, 31, v166
	v_lshrrev_b32_e32 v168, 5, v166
	s_lshl_b32 s24, s54, 8
	v_mul_u32_u24_e32 v169, 0x440, v168
	v_lshl_add_u32 v169, v167, 1, v169
	v_add_u32_e32 v169, s24, v169
	v_lshrrev_b32_e32 v171, 4, v166
	v_and_b32_e32 v178, 15, v166
	v_lshlrev_b32_e32 v179, 8, v171
	v_lshl_add_u32 v179, v178, 4, v179
	v_lshlrev_b32_e32 v174, 10, v168
	v_lshl_add_u32 v174, v167, 1, v174
	v_sub_u32_e32 v174, v179, v174
	v_ashrrev_i32_e32 v175, 31, v174
	v_lshl_add_u64 v[172:173], v[72:73], 0, v[174:175]
	s_mov_b64 s[24:25], 0x1000
	v_lshl_add_u64 v[180:181], v[172:173], 0, s[24:25]
	v_mul_u32_u24_e32 v171, 0x110, v171
	v_lshl_add_u32 v171, v178, 4, v171
	s_lshl_b32 s24, s54, 8
	v_add_u32_e32 v171, s24, v171
	v_cvt_pk_bf16_f32 v179, v48, s0
	ds_write_b16 v169, v179
	v_cvt_pk_bf16_f32 v179, v32, s0
	ds_write_b16 v169, v179 offset:64
	v_cvt_pk_bf16_f32 v179, v16, s0
	ds_write_b16 v169, v179 offset:128
	v_cvt_pk_bf16_f32 v179, v0, s0
	ds_write_b16 v169, v179 offset:192
	v_cvt_pk_bf16_f32 v179, v49, s0
	ds_write_b16 v169, v179 offset:272
	v_cvt_pk_bf16_f32 v179, v33, s0
	ds_write_b16 v169, v179 offset:336
	v_cvt_pk_bf16_f32 v179, v17, s0
	ds_write_b16 v169, v179 offset:400
	v_cvt_pk_bf16_f32 v179, v1, s0
	ds_write_b16 v169, v179 offset:464
	v_cvt_pk_bf16_f32 v179, v50, s0
	ds_write_b16 v169, v179 offset:544
	v_cvt_pk_bf16_f32 v179, v34, s0
	ds_write_b16 v169, v179 offset:608
	v_cvt_pk_bf16_f32 v179, v18, s0
	ds_write_b16 v169, v179 offset:672
	v_cvt_pk_bf16_f32 v179, v2, s0
	ds_write_b16 v169, v179 offset:736
	v_cvt_pk_bf16_f32 v179, v51, s0
	ds_write_b16 v169, v179 offset:816
	v_cvt_pk_bf16_f32 v179, v35, s0
	ds_write_b16 v169, v179 offset:880
	v_cvt_pk_bf16_f32 v179, v19, s0
	ds_write_b16 v169, v179 offset:944
	v_cvt_pk_bf16_f32 v179, v3, s0
	ds_write_b16 v169, v179 offset:1008
	v_cvt_pk_bf16_f32 v179, v52, s0
	ds_write_b16 v169, v179 offset:2176
	v_cvt_pk_bf16_f32 v179, v36, s0
	ds_write_b16 v169, v179 offset:2240
	v_cvt_pk_bf16_f32 v179, v20, s0
	ds_write_b16 v169, v179 offset:2304
	v_cvt_pk_bf16_f32 v179, v4, s0
	ds_write_b16 v169, v179 offset:2368
	v_cvt_pk_bf16_f32 v179, v53, s0
	ds_write_b16 v169, v179 offset:2448
	v_cvt_pk_bf16_f32 v179, v37, s0
	ds_write_b16 v169, v179 offset:2512
	v_cvt_pk_bf16_f32 v179, v21, s0
	ds_write_b16 v169, v179 offset:2576
	v_cvt_pk_bf16_f32 v179, v5, s0
	ds_write_b16 v169, v179 offset:2640
	v_cvt_pk_bf16_f32 v179, v54, s0
	ds_write_b16 v169, v179 offset:2720
	v_cvt_pk_bf16_f32 v179, v38, s0
	ds_write_b16 v169, v179 offset:2784
	v_cvt_pk_bf16_f32 v179, v22, s0
	ds_write_b16 v169, v179 offset:2848
	v_cvt_pk_bf16_f32 v179, v6, s0
	ds_write_b16 v169, v179 offset:2912
	v_cvt_pk_bf16_f32 v179, v55, s0
	ds_write_b16 v169, v179 offset:2992
	v_cvt_pk_bf16_f32 v179, v39, s0
	ds_write_b16 v169, v179 offset:3056
	v_cvt_pk_bf16_f32 v179, v23, s0
	ds_write_b16 v169, v179 offset:3120
	v_cvt_pk_bf16_f32 v179, v7, s0
	ds_write_b16 v169, v179 offset:3184
	v_cvt_pk_bf16_f32 v179, v56, s0
	ds_write_b16 v169, v179 offset:4352
	v_cvt_pk_bf16_f32 v179, v40, s0
	ds_write_b16 v169, v179 offset:4416
	v_cvt_pk_bf16_f32 v179, v24, s0
	ds_write_b16 v169, v179 offset:4480
	v_cvt_pk_bf16_f32 v179, v8, s0
	ds_write_b16 v169, v179 offset:4544
	v_cvt_pk_bf16_f32 v179, v57, s0
	ds_write_b16 v169, v179 offset:4624
	v_cvt_pk_bf16_f32 v179, v41, s0
	ds_write_b16 v169, v179 offset:4688
	v_cvt_pk_bf16_f32 v179, v25, s0
	ds_write_b16 v169, v179 offset:4752
	v_cvt_pk_bf16_f32 v179, v9, s0
	ds_write_b16 v169, v179 offset:4816
	v_cvt_pk_bf16_f32 v179, v58, s0
	ds_write_b16 v169, v179 offset:4896
	v_cvt_pk_bf16_f32 v179, v42, s0
	ds_write_b16 v169, v179 offset:4960
	v_cvt_pk_bf16_f32 v179, v26, s0
	ds_write_b16 v169, v179 offset:5024
	v_cvt_pk_bf16_f32 v179, v10, s0
	ds_write_b16 v169, v179 offset:5088
	v_cvt_pk_bf16_f32 v179, v59, s0
	ds_write_b16 v169, v179 offset:5168
	v_cvt_pk_bf16_f32 v179, v43, s0
	ds_write_b16 v169, v179 offset:5232
	v_cvt_pk_bf16_f32 v179, v27, s0
	ds_write_b16 v169, v179 offset:5296
	v_cvt_pk_bf16_f32 v179, v11, s0
	ds_write_b16 v169, v179 offset:5360
	v_cvt_pk_bf16_f32 v179, v60, s0
	ds_write_b16 v169, v179 offset:6528
	v_cvt_pk_bf16_f32 v179, v44, s0
	ds_write_b16 v169, v179 offset:6592
	v_cvt_pk_bf16_f32 v179, v28, s0
	ds_write_b16 v169, v179 offset:6656
	v_cvt_pk_bf16_f32 v179, v12, s0
	ds_write_b16 v169, v179 offset:6720
	v_cvt_pk_bf16_f32 v179, v61, s0
	ds_write_b16 v169, v179 offset:6800
	v_cvt_pk_bf16_f32 v179, v45, s0
	ds_write_b16 v169, v179 offset:6864
	v_cvt_pk_bf16_f32 v179, v29, s0
	ds_write_b16 v169, v179 offset:6928
	v_cvt_pk_bf16_f32 v179, v13, s0
	ds_write_b16 v169, v179 offset:6992
	v_cvt_pk_bf16_f32 v179, v62, s0
	ds_write_b16 v169, v179 offset:7072
	v_cvt_pk_bf16_f32 v179, v46, s0
	ds_write_b16 v169, v179 offset:7136
	v_cvt_pk_bf16_f32 v179, v30, s0
	ds_write_b16 v169, v179 offset:7200
	v_cvt_pk_bf16_f32 v179, v14, s0
	ds_write_b16 v169, v179 offset:7264
	v_cvt_pk_bf16_f32 v179, v63, s0
	ds_write_b16 v169, v179 offset:7344
	v_cvt_pk_bf16_f32 v179, v47, s0
	ds_write_b16 v169, v179 offset:7408
	v_cvt_pk_bf16_f32 v179, v31, s0
	ds_write_b16 v169, v179 offset:7472
	v_cvt_pk_bf16_f32 v179, v15, s0
	ds_write_b16 v169, v179 offset:7536
	s_waitcnt lgkmcnt(0)
	ds_read_b128 v[134:137], v171
	ds_read_b128 v[138:141], v171 offset:1088
	ds_read_b128 v[142:145], v171 offset:2176
	ds_read_b128 v[146:149], v171 offset:3264
	ds_read_b128 v[150:153], v171 offset:4352
	ds_read_b128 v[154:157], v171 offset:5440
	ds_read_b128 v[158:161], v171 offset:6528
	ds_read_b128 v[162:165], v171 offset:7616
	s_waitcnt lgkmcnt(7)
	global_store_dwordx4 v[172:173], v[134:137], off
	s_waitcnt lgkmcnt(6)
	global_store_dwordx4 v[172:173], v[138:141], off offset:1024
	s_waitcnt lgkmcnt(5)
	global_store_dwordx4 v[172:173], v[142:145], off offset:2048
	s_waitcnt lgkmcnt(4)
	global_store_dwordx4 v[172:173], v[146:149], off offset:3072
	s_waitcnt lgkmcnt(3)
	global_store_dwordx4 v[180:181], v[150:153], off
	s_waitcnt lgkmcnt(2)
	global_store_dwordx4 v[180:181], v[154:157], off offset:1024
	s_waitcnt lgkmcnt(1)
	global_store_dwordx4 v[180:181], v[158:161], off offset:2048
	s_waitcnt lgkmcnt(0)
	global_store_dwordx4 v[180:181], v[162:165], off offset:3072
	v_mbcnt_lo_u32_b32 v0, -1, 0
	v_mbcnt_hi_u32_b32 v0, -1, v0
	s_lshl_b64 s[2:3], s[2:3], 9
	v_lshlrev_b32_e32 v0, 2, v0
	v_xor_b32_e32 v0, 0x80, v0
	ds_bpermute_b32 v0, v0, v81
	s_add_u32 s2, s8, s2
	s_addc_u32 s3, s9, s3
	v_lshlrev_b32_e32 v176, 2, v64
	s_and_saveexec_b64 s[4:5], vcc
	s_cbranch_execz .LBB0_1075
	s_waitcnt lgkmcnt(0)
	v_add_f32_e32 v2, v81, v0
	v_lshl_add_u64 v[0:1], s[2:3], 0, v[176:177]
	flat_store_dword v[0:1], v2
